# non-temporal hint on the read-once streaming loads of the weight-conversion and x->bf16 loops
# speedup vs baseline: 1.0146x; 1.0146x over previous
; #define CVT_LOAD(t_) do { const int k0_ = ((t_) % nkt) * 64, n0_ = ((t_) / nkt) * 64; const int sn = srcmap(kind, n0_ + nl); \
;     _Pragma("unroll") for (int i = 0; i < 8; ++i) { const int kl = kb + 8 * i; v[i] = 0.f; \
;       if (sn >= 0) { v[i] = src[(size_t)(k0_ + kl) * Nsrc + sn]; if (kscale) v[i] *= kscale[k0_ + kl]; } } } while (0)
; __device__ __forceinline__ void cvt_job(LAS unsigned char* lds, const float* src, bf16_t* dst, const float* kscale, int K, int Nsrc, int Ndst, int kind, int wv0, int bid_, int grd_) {
;     ...
;   if (bid_ < ntile) CVT_LOAD(bid_);
;   for (int t = bid_; t < ntile; t += grd_) {
;     const int k0 = (t % nkt) * 64, n0 = (t / nkt) * 64;
; #pragma unroll
;     for (int i = 0; i < 8; ++i) tile[(kb + 8 * i) * 65 + nl] = v[i];
;     __syncthreads();
;     if (t + grd_ < ntile) CVT_LOAD(t + grd_);
.Lmya_r1:
	global_load_dword v176, v146, s[24:25] nt
	global_load_dword v177, v147, s[24:25] nt
	global_load_dword v178, v148, s[24:25] nt
	global_load_dword v179, v149, s[24:25] nt
	global_load_dword v180, v150, s[24:25] nt
	global_load_dword v181, v151, s[24:25] nt
	global_load_dword v182, v152, s[24:25] nt
	global_load_dword v183, v153, s[24:25] nt
	s_branch .Lmya_x1
.Lmya_p1:
	global_load_dword v176, v208, s[24:25] nt
	global_load_dword v177, v209, s[24:25] nt
	global_load_dword v178, v210, s[24:25] nt
	global_load_dword v179, v211, s[24:25] nt
	global_load_dword v180, v212, s[24:25] nt
	global_load_dword v181, v213, s[24:25] nt
	global_load_dword v182, v214, s[24:25] nt
	global_load_dword v183, v215, s[24:25] nt

; #define CVT_LOAD(t_) do { const int k0_ = ((t_) % nkt) * 64, n0_ = ((t_) / nkt) * 64; const int sn = srcmap(kind, n0_ + nl); \
;     _Pragma("unroll") for (int i = 0; i < 8; ++i) { const int kl = kb + 8 * i; v[i] = 0.f; \
;       if (sn >= 0) { v[i] = src[(size_t)(k0_ + kl) * Nsrc + sn]; if (kscale) v[i] *= kscale[k0_ + kl]; } } } while (0)
; __device__ __forceinline__ void cvt_job(LAS unsigned char* lds, const float* src, bf16_t* dst, const float* kscale, int K, int Nsrc, int Ndst, int kind, int wv0, int bid_, int grd_) {
;     ...
;   if (bid_ < ntile) CVT_LOAD(bid_);
;   for (int t = bid_; t < ntile; t += grd_) {
;     const int k0 = (t % nkt) * 64, n0 = (t / nkt) * 64;
; #pragma unroll
;     for (int i = 0; i < 8; ++i) tile[(kb + 8 * i) * 65 + nl] = v[i];
;     __syncthreads();
;     if (t + grd_ < ntile) CVT_LOAD(t + grd_);
.Lmya_r2:
	global_load_dword v184, v146, s[24:25] nt
	global_load_dword v185, v147, s[24:25] nt
	global_load_dword v186, v148, s[24:25] nt
	global_load_dword v187, v149, s[24:25] nt
	global_load_dword v188, v150, s[24:25] nt
	global_load_dword v189, v151, s[24:25] nt
	global_load_dword v190, v152, s[24:25] nt
	global_load_dword v191, v153, s[24:25] nt
	s_branch .Lmya_x2
.Lmya_p2:
	global_load_dword v184, v208, s[24:25] nt
	global_load_dword v185, v209, s[24:25] nt
	global_load_dword v186, v210, s[24:25] nt
	global_load_dword v187, v211, s[24:25] nt
	global_load_dword v188, v212, s[24:25] nt
	global_load_dword v189, v213, s[24:25] nt
	global_load_dword v190, v214, s[24:25] nt
	global_load_dword v191, v215, s[24:25] nt

; #define CVT_LOAD(t_) do { const int k0_ = ((t_) % nkt) * 64, n0_ = ((t_) / nkt) * 64; const int sn = srcmap(kind, n0_ + nl); \
;     _Pragma("unroll") for (int i = 0; i < 8; ++i) { const int kl = kb + 8 * i; v[i] = 0.f; \
;       if (sn >= 0) { v[i] = src[(size_t)(k0_ + kl) * Nsrc + sn]; if (kscale) v[i] *= kscale[k0_ + kl]; } } } while (0)
; __device__ __forceinline__ void cvt_job(LAS unsigned char* lds, const float* src, bf16_t* dst, const float* kscale, int K, int Nsrc, int Ndst, int kind, int wv0, int bid_, int grd_) {
;     ...
;   if (bid_ < ntile) CVT_LOAD(bid_);
;   for (int t = bid_; t < ntile; t += grd_) {
;     const int k0 = (t % nkt) * 64, n0 = (t / nkt) * 64;
; #pragma unroll
;     for (int i = 0; i < 8; ++i) tile[(kb + 8 * i) * 65 + nl] = v[i];
;     __syncthreads();
;     if (t + grd_ < ntile) CVT_LOAD(t + grd_);
.Lmya_r3:
	global_load_dword v192, v146, s[24:25] nt
	global_load_dword v193, v147, s[24:25] nt
	global_load_dword v194, v148, s[24:25] nt
	global_load_dword v195, v149, s[24:25] nt
	global_load_dword v196, v150, s[24:25] nt
	global_load_dword v197, v151, s[24:25] nt
	global_load_dword v198, v152, s[24:25] nt
	global_load_dword v199, v153, s[24:25] nt
	s_branch .Lmya_x3
.Lmya_p3:
	global_load_dword v192, v208, s[24:25] nt
	global_load_dword v193, v209, s[24:25] nt
	global_load_dword v194, v210, s[24:25] nt
	global_load_dword v195, v211, s[24:25] nt
	global_load_dword v196, v212, s[24:25] nt
	global_load_dword v197, v213, s[24:25] nt
	global_load_dword v198, v214, s[24:25] nt
	global_load_dword v199, v215, s[24:25] nt

; #define CVT_LOAD(t_) do { const int k0_ = ((t_) % nkt) * 64, n0_ = ((t_) / nkt) * 64; const int sn = srcmap(kind, n0_ + nl); \
;     _Pragma("unroll") for (int i = 0; i < 8; ++i) { const int kl = kb + 8 * i; v[i] = 0.f; \
;       if (sn >= 0) { v[i] = src[(size_t)(k0_ + kl) * Nsrc + sn]; if (kscale) v[i] *= kscale[k0_ + kl]; } } } while (0)
; __device__ __forceinline__ void cvt_job(LAS unsigned char* lds, const float* src, bf16_t* dst, const float* kscale, int K, int Nsrc, int Ndst, int kind, int wv0, int bid_, int grd_) {
;     ...
;   if (bid_ < ntile) CVT_LOAD(bid_);
;   for (int t = bid_; t < ntile; t += grd_) {
;     const int k0 = (t % nkt) * 64, n0 = (t / nkt) * 64;
; #pragma unroll
;     for (int i = 0; i < 8; ++i) tile[(kb + 8 * i) * 65 + nl] = v[i];
;     __syncthreads();
;     if (t + grd_ < ntile) CVT_LOAD(t + grd_);
.Lmya_r4:
	global_load_dword v200, v146, s[24:25] nt
	global_load_dword v201, v147, s[24:25] nt
	global_load_dword v202, v148, s[24:25] nt
	global_load_dword v203, v149, s[24:25] nt
	global_load_dword v204, v150, s[24:25] nt
	global_load_dword v205, v151, s[24:25] nt
	global_load_dword v206, v152, s[24:25] nt
	global_load_dword v207, v153, s[24:25] nt
	s_branch .Lmya_x4
.Lmya_p4:
	global_load_dword v200, v208, s[24:25] nt
	global_load_dword v201, v209, s[24:25] nt
	global_load_dword v202, v210, s[24:25] nt
	global_load_dword v203, v211, s[24:25] nt
	global_load_dword v204, v212, s[24:25] nt
	global_load_dword v205, v213, s[24:25] nt
	global_load_dword v206, v214, s[24:25] nt
	global_load_dword v207, v215, s[24:25] nt

; #define CVT_LOAD(t_) do { const int k0_ = ((t_) % nkt) * 64, n0_ = ((t_) / nkt) * 64; const int sn = srcmap(kind, n0_ + nl); \
;     _Pragma("unroll") for (int i = 0; i < 8; ++i) { const int kl = kb + 8 * i; v[i] = 0.f; \
;       if (sn >= 0) { v[i] = src[(size_t)(k0_ + kl) * Nsrc + sn]; if (kscale) v[i] *= kscale[k0_ + kl]; } } } while (0)
; __device__ __forceinline__ void cvt_job(LAS unsigned char* lds, const float* src, bf16_t* dst, const float* kscale, int K, int Nsrc, int Ndst, int kind, int wv0, int bid_, int grd_) {
;     ...
;   if (bid_ < ntile) CVT_LOAD(bid_);
;   for (int t = bid_; t < ntile; t += grd_) {
;     const int k0 = (t % nkt) * 64, n0 = (t / nkt) * 64;
; #pragma unroll
;     for (int i = 0; i < 8; ++i) tile[(kb + 8 * i) * 65 + nl] = v[i];
;     __syncthreads();
;     if (t + grd_ < ntile) CVT_LOAD(t + grd_);
; __device__ __forceinline__ void cvt_mixer_a(KP p, int l, LAS unsigned char* lds, int wv0) {
;     ...
;   cvt_job(lds, p->w_in + (size_t)l * DM * NIN, (bf16_t*)(W + O_WMAIN), nullptr, DM, NIN, NHP, 1, wv0, f, st);
;   cvt_job(lds, p->w_in + (size_t)l * DM * NIN, (bf16_t*)(W + O_WG), nullptr, DM, NIN, NG, 2, wv0, f, st);
.Lmya_end:
	s_waitcnt vmcnt(0)
	s_add_u32 s18, s8, 0x1200000
	s_addc_u32 s19, s9, 0
	v_mbcnt_lo_u32_b32 v235, -1, 0
	v_mbcnt_hi_u32_b32 v235, -1, v235
	v_or_b32_e32 v235, s0, v235
	v_and_b32_e32 v236, 63, v235
	v_lshrrev_b32_e32 v216, 6, v235
	s_mov_b32 s30, 0xa500
	v_mul_lo_u32 v208, v216, s30
	v_lshl_add_u32 v208, v236, 2, v208
	v_add_u32_e32 v209, 0x52800, v208
	v_add_u32_e32 v210, 0xa5000, v208
	v_add_u32_e32 v211, 0xf7800, v208
	v_add_u32_e32 v212, 0x14a000, v208
	v_add_u32_e32 v213, 0x19c800, v208
	v_add_u32_e32 v214, 0x1ef000, v208
	v_add_u32_e32 v215, 0x241800, v208
	v_mul_u32_u24_e32 v216, 65, v216
	v_add_lshl_u32 v216, v216, v236, 2
	v_and_b32_e32 v236, 7, v235
	v_lshlrev_b32_e32 v236, 3, v236
	v_lshrrev_b32_e32 v235, 3, v235
	v_mul_u32_u24_e32 v217, 65, v236
	v_add_lshl_u32 v217, v217, v235, 2
	s_movk_i32 s30, 0x800
	v_mul_lo_u32 v234, v235, s30
	v_add_lshl_u32 v234, v234, v236, 1
	s_mov_b32 s20, s82
	s_lshl_b32 s21, s60, 2
	s_mov_b32 s23, 0
	s_add_u32 s23, s23, s20
	s_and_b32 s28, s23, 31
	s_lshr_b32 s29, s23, 5
	s_lshl_b32 s28, s28, 6
	s_lshl_b32 s29, s29, 6
	s_mov_b32 s13, 0
	s_add_u32 s31, s29, 0x1140
	s_mul_i32 s12, s28, 0xa500
	s_lshl_b32 s31, s31, 2
	s_add_u32 s12, s12, s31
	s_add_u32 s24, s16, s12
	s_addc_u32 s25, s17, 0
	s_cmp_lt_u32 s23, 0xc00
	s_cbranch_scc0 .Lmyg_pl
	global_load_dword v176, v208, s[24:25] nt
	global_load_dword v177, v209, s[24:25] nt
	global_load_dword v178, v210, s[24:25] nt
	global_load_dword v179, v211, s[24:25] nt
	global_load_dword v180, v212, s[24:25] nt
	global_load_dword v181, v213, s[24:25] nt
	global_load_dword v182, v214, s[24:25] nt
	global_load_dword v183, v215, s[24:25] nt
	s_mul_i32 s23, s60, 1
	s_add_u32 s23, s23, s20
	s_and_b32 s28, s23, 31
	s_lshr_b32 s29, s23, 5
	s_lshl_b32 s28, s28, 6
	s_lshl_b32 s29, s29, 6
	s_mov_b32 s13, 0
	s_add_u32 s31, s29, 0x1140
	s_mul_i32 s12, s28, 0xa500
	s_lshl_b32 s31, s31, 2
	s_add_u32 s12, s12, s31
	s_add_u32 s24, s16, s12
	s_addc_u32 s25, s17, 0
	s_cmp_lt_u32 s23, 0xc00
	s_cbranch_scc0 .Lmyg_pl
	global_load_dword v184, v208, s[24:25] nt
	global_load_dword v185, v209, s[24:25] nt
	global_load_dword v186, v210, s[24:25] nt
	global_load_dword v187, v211, s[24:25] nt
	global_load_dword v188, v212, s[24:25] nt
	global_load_dword v189, v213, s[24:25] nt
	global_load_dword v190, v214, s[24:25] nt
	global_load_dword v191, v215, s[24:25] nt
	s_mul_i32 s23, s60, 2
	s_add_u32 s23, s23, s20
	s_and_b32 s28, s23, 31
	s_lshr_b32 s29, s23, 5
	s_lshl_b32 s28, s28, 6
	s_lshl_b32 s29, s29, 6
	s_mov_b32 s13, 0
	s_add_u32 s31, s29, 0x1140
	s_mul_i32 s12, s28, 0xa500
	s_lshl_b32 s31, s31, 2
	s_add_u32 s12, s12, s31
	s_add_u32 s24, s16, s12
	s_addc_u32 s25, s17, 0
	s_cmp_lt_u32 s23, 0xc00
	s_cbranch_scc0 .Lmyg_pl
	global_load_dword v192, v208, s[24:25] nt
	global_load_dword v193, v209, s[24:25] nt
	global_load_dword v194, v210, s[24:25] nt
	global_load_dword v195, v211, s[24:25] nt
	global_load_dword v196, v212, s[24:25] nt
	global_load_dword v197, v213, s[24:25] nt
	global_load_dword v198, v214, s[24:25] nt
	global_load_dword v199, v215, s[24:25] nt
	s_mul_i32 s23, s60, 3
	s_add_u32 s23, s23, s20
	s_and_b32 s28, s23, 31
	s_lshr_b32 s29, s23, 5
	s_lshl_b32 s28, s28, 6
	s_lshl_b32 s29, s29, 6
	s_mov_b32 s13, 0
	s_add_u32 s31, s29, 0x1140
	s_mul_i32 s12, s28, 0xa500
	s_lshl_b32 s31, s31, 2
	s_add_u32 s12, s12, s31
	s_add_u32 s24, s16, s12
	s_addc_u32 s25, s17, 0
	s_cmp_lt_u32 s23, 0xc00
	s_cbranch_scc0 .Lmyg_pl
	global_load_dword v200, v208, s[24:25] nt
	global_load_dword v201, v209, s[24:25] nt
	global_load_dword v202, v210, s[24:25] nt
	global_load_dword v203, v211, s[24:25] nt
	global_load_dword v204, v212, s[24:25] nt
	global_load_dword v205, v213, s[24:25] nt
	global_load_dword v206, v214, s[24:25] nt
	global_load_dword v207, v215, s[24:25] nt

; #define CVT_LOAD(t_) do { const int k0_ = ((t_) % nkt) * 64, n0_ = ((t_) / nkt) * 64; const int sn = srcmap(kind, n0_ + nl); \
;     _Pragma("unroll") for (int i = 0; i < 8; ++i) { const int kl = kb + 8 * i; v[i] = 0.f; \
;       if (sn >= 0) { v[i] = src[(size_t)(k0_ + kl) * Nsrc + sn]; if (kscale) v[i] *= kscale[k0_ + kl]; } } } while (0)
; __device__ __forceinline__ void cvt_job(LAS unsigned char* lds, const float* src, bf16_t* dst, const float* kscale, int K, int Nsrc, int Ndst, int kind, int wv0, int bid_, int grd_) {
;     ...
;   for (int t = bid_; t < ntile; t += grd_) {
;     const int k0 = (t % nkt) * 64, n0 = (t / nkt) * 64;
; #pragma unroll
;     for (int i = 0; i < 8; ++i) tile[(kb + 8 * i) * 65 + nl] = v[i];
;     __syncthreads();
;     if (t + grd_ < ntile) CVT_LOAD(t + grd_);
.Lmyg_wd:
	s_waitcnt lgkmcnt(0)
	s_barrier
	s_add_u32 s20, s20, s21
	s_mov_b32 s23, 0
	s_add_u32 s23, s23, s20
	s_and_b32 s28, s23, 31
	s_lshr_b32 s29, s23, 5
	s_lshl_b32 s28, s28, 6
	s_lshl_b32 s29, s29, 6
	s_mov_b32 s13, 0
	s_add_u32 s31, s29, 0x1140
	s_mul_i32 s12, s28, 0xa500
	s_lshl_b32 s31, s31, 2
	s_add_u32 s12, s12, s31
	s_add_u32 s24, s16, s12
	s_addc_u32 s25, s17, 0
	s_cmp_lt_u32 s23, 0xc00
	s_cbranch_scc0 .Lmyg_nl
	global_load_dword v176, v208, s[24:25] nt
	global_load_dword v177, v209, s[24:25] nt
	global_load_dword v178, v210, s[24:25] nt
	global_load_dword v179, v211, s[24:25] nt
	global_load_dword v180, v212, s[24:25] nt
	global_load_dword v181, v213, s[24:25] nt
	global_load_dword v182, v214, s[24:25] nt
	global_load_dword v183, v215, s[24:25] nt
	s_mul_i32 s23, s60, 1
	s_add_u32 s23, s23, s20
	s_and_b32 s28, s23, 31
	s_lshr_b32 s29, s23, 5
	s_lshl_b32 s28, s28, 6
	s_lshl_b32 s29, s29, 6
	s_mov_b32 s13, 0
	s_add_u32 s31, s29, 0x1140
	s_mul_i32 s12, s28, 0xa500
	s_lshl_b32 s31, s31, 2
	s_add_u32 s12, s12, s31
	s_add_u32 s24, s16, s12
	s_addc_u32 s25, s17, 0
	s_cmp_lt_u32 s23, 0xc00
	s_cbranch_scc0 .Lmyg_nl
	global_load_dword v184, v208, s[24:25] nt
	global_load_dword v185, v209, s[24:25] nt
	global_load_dword v186, v210, s[24:25] nt
	global_load_dword v187, v211, s[24:25] nt
	global_load_dword v188, v212, s[24:25] nt
	global_load_dword v189, v213, s[24:25] nt
	global_load_dword v190, v214, s[24:25] nt
	global_load_dword v191, v215, s[24:25] nt
	s_mul_i32 s23, s60, 2
	s_add_u32 s23, s23, s20
	s_and_b32 s28, s23, 31
	s_lshr_b32 s29, s23, 5
	s_lshl_b32 s28, s28, 6
	s_lshl_b32 s29, s29, 6
	s_mov_b32 s13, 0
	s_add_u32 s31, s29, 0x1140
	s_mul_i32 s12, s28, 0xa500
	s_lshl_b32 s31, s31, 2
	s_add_u32 s12, s12, s31
	s_add_u32 s24, s16, s12
	s_addc_u32 s25, s17, 0
	s_cmp_lt_u32 s23, 0xc00
	s_cbranch_scc0 .Lmyg_nl
	global_load_dword v192, v208, s[24:25] nt
	global_load_dword v193, v209, s[24:25] nt
	global_load_dword v194, v210, s[24:25] nt
	global_load_dword v195, v211, s[24:25] nt
	global_load_dword v196, v212, s[24:25] nt
	global_load_dword v197, v213, s[24:25] nt
	global_load_dword v198, v214, s[24:25] nt
	global_load_dword v199, v215, s[24:25] nt
	s_mul_i32 s23, s60, 3
	s_add_u32 s23, s23, s20
	s_and_b32 s28, s23, 31
	s_lshr_b32 s29, s23, 5
	s_lshl_b32 s28, s28, 6
	s_lshl_b32 s29, s29, 6
	s_mov_b32 s13, 0
	s_add_u32 s31, s29, 0x1140
	s_mul_i32 s12, s28, 0xa500
	s_lshl_b32 s31, s31, 2
	s_add_u32 s12, s12, s31
	s_add_u32 s24, s16, s12
	s_addc_u32 s25, s17, 0
	s_cmp_lt_u32 s23, 0xc00
	s_cbranch_scc0 .Lmyg_nl
	global_load_dword v200, v208, s[24:25] nt
	global_load_dword v201, v209, s[24:25] nt
	global_load_dword v202, v210, s[24:25] nt
	global_load_dword v203, v211, s[24:25] nt
	global_load_dword v204, v212, s[24:25] nt
	global_load_dword v205, v213, s[24:25] nt
	global_load_dword v206, v214, s[24:25] nt
	global_load_dword v207, v215, s[24:25] nt

; __device__ __forceinline__ int otid(int wv0) { int t = (wv0 << 6) | olane(); asm volatile("" : "+v"(t)); return t; }
; __device__ __forceinline__ int obid() { int b = blockIdx.x; asm volatile("" : "+s"(b)); return b; }
; __device__ __forceinline__ int ogrid() { int g = gridDim.x; asm volatile("" : "+s"(g)); return g; }
; __device__ __forceinline__ void prologue(KP p, int wv0) {
;   const size_t tid = (size_t)obid() * 512 + otid(wv0), nth = (size_t)ogrid() * 512;
;   bf16_t* xb = (bf16_t*)(p->ws + O_XB);
;   for (size_t i = tid; i < (size_t)NTOK * DM / 4; i += 4 * nth) {
;     f32x4 v[4];
; #pragma unroll
;     for (int j = 0; j < 4; ++j) if (i + j * nth < (size_t)NTOK * DM / 4) v[j] = ((const f32x4*)p->x)[i + j * nth];
; #pragma unroll
;     for (int j = 0; j < 4; ++j) if (i + j * nth < (size_t)NTOK * DM / 4) { u32x2 w; w.x = pk2(v[j][0], v[j][1]); w.y = pk2(v[j][2], v[j][3]); ((u32x2*)xb)[i + j * nth] = w; } }
.LBB0_106:
	s_mov_b32 s12, s82
	s_mov_b32 s1, -1
	s_ashr_i32 s13, s12, 31
	s_waitcnt vmcnt(1)
	v_mbcnt_lo_u32_b32 v1, s1, 0
	v_mbcnt_hi_u32_b32 v1, s1, v1
	v_or_b32_e32 v20, s0, v1
	s_waitcnt lgkmcnt(0)
	s_lshl_b64 s[2:3], s[12:13], 9
	s_mov_b32 s14, s60
	v_ashrrev_i32_e32 v21, 31, v20
	v_lshl_add_u64 v[18:19], s[2:3], 0, v[20:21]
	s_ashr_i32 s15, s14, 31
	s_mov_b64 s[16:17], 0x800000
	s_lshl_b64 s[10:11], s[14:15], 9
	v_cmp_gt_u64_e32 vcc, s[16:17], v[18:19]
	s_and_saveexec_b64 s[18:19], vcc
	s_cbranch_execz .LBB0_121
	s_cmp_eq_u32 s60, 0x100
	s_cbranch_scc0 .Lx2b_orig
	s_load_dwordx2 s[20:21], s[54:55], 0x0
	v_lshlrev_b32_e32 v64, 4, v18
	v_lshlrev_b32_e32 v72, 3, v18
	v_add_u32_e32 v65, 0x200000, v64
	v_add_u32_e32 v73, 0x100000, v72
	v_add_u32_e32 v66, 0x400000, v64
	v_add_u32_e32 v74, 0x200000, v72
	v_add_u32_e32 v67, 0x600000, v64
	v_add_u32_e32 v75, 0x300000, v72
	v_add_u32_e32 v68, 0x800000, v64
	v_add_u32_e32 v76, 0x400000, v72
	v_add_u32_e32 v69, 0xa00000, v64
	v_add_u32_e32 v77, 0x500000, v72
	v_add_u32_e32 v70, 0xc00000, v64
	v_add_u32_e32 v78, 0x600000, v72
	v_add_u32_e32 v71, 0xe00000, v64
	v_add_u32_e32 v79, 0x700000, v72
	s_add_u32 s22, s8, 0x4900000
	s_addc_u32 s23, s9, 0
	s_waitcnt lgkmcnt(0)
	s_add_u32 s24, s20, 0x0
	s_addc_u32 s25, s21, 0
	global_load_dwordx4 v[2:5], v64, s[24:25] nt
	global_load_dwordx4 v[6:9], v65, s[24:25] nt
	global_load_dwordx4 v[10:13], v66, s[24:25] nt
	global_load_dwordx4 v[14:17], v67, s[24:25] nt
	global_load_dwordx4 v[22:25], v68, s[24:25] nt
	global_load_dwordx4 v[26:29], v69, s[24:25] nt
	global_load_dwordx4 v[30:33], v70, s[24:25] nt
	global_load_dwordx4 v[34:37], v71, s[24:25] nt
	s_add_u32 s24, s20, 0x1000000
	s_addc_u32 s25, s21, 0
	global_load_dwordx4 v[48:51], v64, s[24:25] nt
	global_load_dwordx4 v[52:55], v65, s[24:25] nt
	global_load_dwordx4 v[56:59], v66, s[24:25] nt
	global_load_dwordx4 v[60:63], v67, s[24:25] nt
	global_load_dwordx4 v[100:103], v68, s[24:25] nt
	global_load_dwordx4 v[104:107], v69, s[24:25] nt
	global_load_dwordx4 v[108:111], v70, s[24:25] nt
	global_load_dwordx4 v[112:115], v71, s[24:25] nt
	s_waitcnt vmcnt(8)
	v_cvt_pk_bf16_f32 v2, v2, v3
	v_cvt_pk_bf16_f32 v3, v4, v5
	v_cvt_pk_bf16_f32 v6, v6, v7
	v_cvt_pk_bf16_f32 v7, v8, v9
	v_cvt_pk_bf16_f32 v10, v10, v11
	v_cvt_pk_bf16_f32 v11, v12, v13
	v_cvt_pk_bf16_f32 v14, v14, v15
	v_cvt_pk_bf16_f32 v15, v16, v17
	v_cvt_pk_bf16_f32 v22, v22, v23
	v_cvt_pk_bf16_f32 v23, v24, v25
	v_cvt_pk_bf16_f32 v26, v26, v27
	v_cvt_pk_bf16_f32 v27, v28, v29
	v_cvt_pk_bf16_f32 v30, v30, v31
	v_cvt_pk_bf16_f32 v31, v32, v33
	v_cvt_pk_bf16_f32 v34, v34, v35
	v_cvt_pk_bf16_f32 v35, v36, v37
	s_add_u32 s26, s22, 0x0
	s_addc_u32 s27, s23, 0
	global_store_dwordx2 v72, v[2:3], s[26:27]
	global_store_dwordx2 v73, v[6:7], s[26:27]
	global_store_dwordx2 v74, v[10:11], s[26:27]
	global_store_dwordx2 v75, v[14:15], s[26:27]
	global_store_dwordx2 v76, v[22:23], s[26:27]
	global_store_dwordx2 v77, v[26:27], s[26:27]
	global_store_dwordx2 v78, v[30:31], s[26:27]
	global_store_dwordx2 v79, v[34:35], s[26:27]
	s_add_u32 s24, s20, 0x2000000
	s_addc_u32 s25, s21, 0
	global_load_dwordx4 v[2:5], v64, s[24:25] nt
	global_load_dwordx4 v[6:9], v65, s[24:25] nt
	global_load_dwordx4 v[10:13], v66, s[24:25] nt
	global_load_dwordx4 v[14:17], v67, s[24:25] nt
	global_load_dwordx4 v[22:25], v68, s[24:25] nt
	global_load_dwordx4 v[26:29], v69, s[24:25] nt
	global_load_dwordx4 v[30:33], v70, s[24:25] nt
	global_load_dwordx4 v[34:37], v71, s[24:25] nt
	s_waitcnt vmcnt(16)
	v_cvt_pk_bf16_f32 v48, v48, v49
	v_cvt_pk_bf16_f32 v49, v50, v51
	v_cvt_pk_bf16_f32 v52, v52, v53
	v_cvt_pk_bf16_f32 v53, v54, v55
	v_cvt_pk_bf16_f32 v56, v56, v57
	v_cvt_pk_bf16_f32 v57, v58, v59
	v_cvt_pk_bf16_f32 v60, v60, v61
	v_cvt_pk_bf16_f32 v61, v62, v63
	v_cvt_pk_bf16_f32 v100, v100, v101
	v_cvt_pk_bf16_f32 v101, v102, v103
	v_cvt_pk_bf16_f32 v104, v104, v105
	v_cvt_pk_bf16_f32 v105, v106, v107
	v_cvt_pk_bf16_f32 v108, v108, v109
	v_cvt_pk_bf16_f32 v109, v110, v111
	v_cvt_pk_bf16_f32 v112, v112, v113
	v_cvt_pk_bf16_f32 v113, v114, v115
	s_add_u32 s26, s22, 0x800000
	s_addc_u32 s27, s23, 0
	global_store_dwordx2 v72, v[48:49], s[26:27]
	global_store_dwordx2 v73, v[52:53], s[26:27]
	global_store_dwordx2 v74, v[56:57], s[26:27]
	global_store_dwordx2 v75, v[60:61], s[26:27]
	global_store_dwordx2 v76, v[100:101], s[26:27]
	global_store_dwordx2 v77, v[104:105], s[26:27]
	global_store_dwordx2 v78, v[108:109], s[26:27]
	global_store_dwordx2 v79, v[112:113], s[26:27]
	s_add_u32 s24, s20, 0x3000000
	s_addc_u32 s25, s21, 0
	global_load_dwordx4 v[48:51], v64, s[24:25] nt
	global_load_dwordx4 v[52:55], v65, s[24:25] nt
	global_load_dwordx4 v[56:59], v66, s[24:25] nt
	global_load_dwordx4 v[60:63], v67, s[24:25] nt
	global_load_dwordx4 v[100:103], v68, s[24:25] nt
	global_load_dwordx4 v[104:107], v69, s[24:25] nt
	global_load_dwordx4 v[108:111], v70, s[24:25] nt
	global_load_dwordx4 v[112:115], v71, s[24:25] nt
	s_waitcnt vmcnt(16)
; __device__ __forceinline__ void prologue(KP p, int wv0) {
;     ...
;   for (size_t i = tid; i < (size_t)NTOK * DM / 4; i += 4 * nth) {
;     f32x4 v[4];
; #pragma unroll
;     for (int j = 0; j < 4; ++j) if (i + j * nth < (size_t)NTOK * DM / 4) v[j] = ((const f32x4*)p->x)[i + j * nth];
; #pragma unroll
;     for (int j = 0; j < 4; ++j) if (i + j * nth < (size_t)NTOK * DM / 4) { u32x2 w; w.x = pk2(v[j][0], v[j][1]); w.y = pk2(v[j][2], v[j][3]); ((u32x2*)xb)[i + j * nth] = w; } }
	v_cvt_pk_bf16_f32 v2, v2, v3
	v_cvt_pk_bf16_f32 v3, v4, v5
	v_cvt_pk_bf16_f32 v6, v6, v7
	v_cvt_pk_bf16_f32 v7, v8, v9
	v_cvt_pk_bf16_f32 v10, v10, v11
	v_cvt_pk_bf16_f32 v11, v12, v13
	v_cvt_pk_bf16_f32 v14, v14, v15
	v_cvt_pk_bf16_f32 v15, v16, v17
	v_cvt_pk_bf16_f32 v22, v22, v23
	v_cvt_pk_bf16_f32 v23, v24, v25
	v_cvt_pk_bf16_f32 v26, v26, v27
	v_cvt_pk_bf16_f32 v27, v28, v29
	v_cvt_pk_bf16_f32 v30, v30, v31
	v_cvt_pk_bf16_f32 v31, v32, v33
	v_cvt_pk_bf16_f32 v34, v34, v35
	v_cvt_pk_bf16_f32 v35, v36, v37
	s_add_u32 s26, s22, 0x1000000
	s_addc_u32 s27, s23, 0
	global_store_dwordx2 v72, v[2:3], s[26:27]
	global_store_dwordx2 v73, v[6:7], s[26:27]
	global_store_dwordx2 v74, v[10:11], s[26:27]
	global_store_dwordx2 v75, v[14:15], s[26:27]
	global_store_dwordx2 v76, v[22:23], s[26:27]
	global_store_dwordx2 v77, v[26:27], s[26:27]
	global_store_dwordx2 v78, v[30:31], s[26:27]
	global_store_dwordx2 v79, v[34:35], s[26:27]
	s_add_u32 s24, s20, 0x4000000
	s_addc_u32 s25, s21, 0
	global_load_dwordx4 v[2:5], v64, s[24:25] nt
	global_load_dwordx4 v[6:9], v65, s[24:25] nt
	global_load_dwordx4 v[10:13], v66, s[24:25] nt
	global_load_dwordx4 v[14:17], v67, s[24:25] nt
	global_load_dwordx4 v[22:25], v68, s[24:25] nt
	global_load_dwordx4 v[26:29], v69, s[24:25] nt
	global_load_dwordx4 v[30:33], v70, s[24:25] nt
	global_load_dwordx4 v[34:37], v71, s[24:25] nt
	s_waitcnt vmcnt(16)
	v_cvt_pk_bf16_f32 v48, v48, v49
	v_cvt_pk_bf16_f32 v49, v50, v51
	v_cvt_pk_bf16_f32 v52, v52, v53
	v_cvt_pk_bf16_f32 v53, v54, v55
	v_cvt_pk_bf16_f32 v56, v56, v57
	v_cvt_pk_bf16_f32 v57, v58, v59
	v_cvt_pk_bf16_f32 v60, v60, v61
	v_cvt_pk_bf16_f32 v61, v62, v63
	v_cvt_pk_bf16_f32 v100, v100, v101
	v_cvt_pk_bf16_f32 v101, v102, v103
	v_cvt_pk_bf16_f32 v104, v104, v105
	v_cvt_pk_bf16_f32 v105, v106, v107
	v_cvt_pk_bf16_f32 v108, v108, v109
	v_cvt_pk_bf16_f32 v109, v110, v111
	v_cvt_pk_bf16_f32 v112, v112, v113
	v_cvt_pk_bf16_f32 v113, v114, v115
	s_add_u32 s26, s22, 0x1800000
	s_addc_u32 s27, s23, 0
	global_store_dwordx2 v72, v[48:49], s[26:27]
	global_store_dwordx2 v73, v[52:53], s[26:27]
	global_store_dwordx2 v74, v[56:57], s[26:27]
	global_store_dwordx2 v75, v[60:61], s[26:27]
	global_store_dwordx2 v76, v[100:101], s[26:27]
	global_store_dwordx2 v77, v[104:105], s[26:27]
	global_store_dwordx2 v78, v[108:109], s[26:27]
	global_store_dwordx2 v79, v[112:113], s[26:27]
	s_add_u32 s24, s20, 0x5000000
	s_addc_u32 s25, s21, 0
	global_load_dwordx4 v[48:51], v64, s[24:25] nt
	global_load_dwordx4 v[52:55], v65, s[24:25] nt
	global_load_dwordx4 v[56:59], v66, s[24:25] nt
	global_load_dwordx4 v[60:63], v67, s[24:25] nt
	global_load_dwordx4 v[100:103], v68, s[24:25] nt
	global_load_dwordx4 v[104:107], v69, s[24:25] nt
	global_load_dwordx4 v[108:111], v70, s[24:25] nt
	global_load_dwordx4 v[112:115], v71, s[24:25] nt
	s_waitcnt vmcnt(16)
	v_cvt_pk_bf16_f32 v2, v2, v3
	v_cvt_pk_bf16_f32 v3, v4, v5
	v_cvt_pk_bf16_f32 v6, v6, v7
	v_cvt_pk_bf16_f32 v7, v8, v9
	v_cvt_pk_bf16_f32 v10, v10, v11
	v_cvt_pk_bf16_f32 v11, v12, v13
	v_cvt_pk_bf16_f32 v14, v14, v15
	v_cvt_pk_bf16_f32 v15, v16, v17
	v_cvt_pk_bf16_f32 v22, v22, v23
	v_cvt_pk_bf16_f32 v23, v24, v25
	v_cvt_pk_bf16_f32 v26, v26, v27
	v_cvt_pk_bf16_f32 v27, v28, v29
	v_cvt_pk_bf16_f32 v30, v30, v31
	v_cvt_pk_bf16_f32 v31, v32, v33
	v_cvt_pk_bf16_f32 v34, v34, v35
	v_cvt_pk_bf16_f32 v35, v36, v37
	s_add_u32 s26, s22, 0x2000000
	s_addc_u32 s27, s23, 0
	global_store_dwordx2 v72, v[2:3], s[26:27]
	global_store_dwordx2 v73, v[6:7], s[26:27]
	global_store_dwordx2 v74, v[10:11], s[26:27]
	global_store_dwordx2 v75, v[14:15], s[26:27]
	global_store_dwordx2 v76, v[22:23], s[26:27]
	global_store_dwordx2 v77, v[26:27], s[26:27]
	global_store_dwordx2 v78, v[30:31], s[26:27]
	global_store_dwordx2 v79, v[34:35], s[26:27]
	s_add_u32 s24, s20, 0x6000000
	s_addc_u32 s25, s21, 0
	global_load_dwordx4 v[2:5], v64, s[24:25] nt
	global_load_dwordx4 v[6:9], v65, s[24:25] nt
	global_load_dwordx4 v[10:13], v66, s[24:25] nt
	global_load_dwordx4 v[14:17], v67, s[24:25] nt
	global_load_dwordx4 v[22:25], v68, s[24:25] nt
	global_load_dwordx4 v[26:29], v69, s[24:25] nt
	global_load_dwordx4 v[30:33], v70, s[24:25] nt
	global_load_dwordx4 v[34:37], v71, s[24:25] nt
	s_waitcnt vmcnt(16)
; __device__ __forceinline__ void prologue(KP p, int wv0) {
;     ...
;   for (size_t i = tid; i < (size_t)NTOK * DM / 4; i += 4 * nth) {
;     f32x4 v[4];
; #pragma unroll
;     for (int j = 0; j < 4; ++j) if (i + j * nth < (size_t)NTOK * DM / 4) v[j] = ((const f32x4*)p->x)[i + j * nth];
; #pragma unroll
;     for (int j = 0; j < 4; ++j) if (i + j * nth < (size_t)NTOK * DM / 4) { u32x2 w; w.x = pk2(v[j][0], v[j][1]); w.y = pk2(v[j][2], v[j][3]); ((u32x2*)xb)[i + j * nth] = w; } }
	v_cvt_pk_bf16_f32 v48, v48, v49
	v_cvt_pk_bf16_f32 v49, v50, v51
	v_cvt_pk_bf16_f32 v52, v52, v53
	v_cvt_pk_bf16_f32 v53, v54, v55
	v_cvt_pk_bf16_f32 v56, v56, v57
	v_cvt_pk_bf16_f32 v57, v58, v59
	v_cvt_pk_bf16_f32 v60, v60, v61
	v_cvt_pk_bf16_f32 v61, v62, v63
	v_cvt_pk_bf16_f32 v100, v100, v101
	v_cvt_pk_bf16_f32 v101, v102, v103
	v_cvt_pk_bf16_f32 v104, v104, v105
	v_cvt_pk_bf16_f32 v105, v106, v107
	v_cvt_pk_bf16_f32 v108, v108, v109
	v_cvt_pk_bf16_f32 v109, v110, v111
	v_cvt_pk_bf16_f32 v112, v112, v113
	v_cvt_pk_bf16_f32 v113, v114, v115
	s_add_u32 s26, s22, 0x2800000
	s_addc_u32 s27, s23, 0
	global_store_dwordx2 v72, v[48:49], s[26:27]
	global_store_dwordx2 v73, v[52:53], s[26:27]
	global_store_dwordx2 v74, v[56:57], s[26:27]
	global_store_dwordx2 v75, v[60:61], s[26:27]
	global_store_dwordx2 v76, v[100:101], s[26:27]
	global_store_dwordx2 v77, v[104:105], s[26:27]
	global_store_dwordx2 v78, v[108:109], s[26:27]
	global_store_dwordx2 v79, v[112:113], s[26:27]
	s_add_u32 s24, s20, 0x7000000
	s_addc_u32 s25, s21, 0
	global_load_dwordx4 v[48:51], v64, s[24:25] nt
	global_load_dwordx4 v[52:55], v65, s[24:25] nt
	global_load_dwordx4 v[56:59], v66, s[24:25] nt
	global_load_dwordx4 v[60:63], v67, s[24:25] nt
	global_load_dwordx4 v[100:103], v68, s[24:25] nt
	global_load_dwordx4 v[104:107], v69, s[24:25] nt
	global_load_dwordx4 v[108:111], v70, s[24:25] nt
	global_load_dwordx4 v[112:115], v71, s[24:25] nt
	s_waitcnt vmcnt(16)
	v_cvt_pk_bf16_f32 v2, v2, v3
	v_cvt_pk_bf16_f32 v3, v4, v5
	v_cvt_pk_bf16_f32 v6, v6, v7
	v_cvt_pk_bf16_f32 v7, v8, v9
	v_cvt_pk_bf16_f32 v10, v10, v11
	v_cvt_pk_bf16_f32 v11, v12, v13
	v_cvt_pk_bf16_f32 v14, v14, v15
	v_cvt_pk_bf16_f32 v15, v16, v17
	v_cvt_pk_bf16_f32 v22, v22, v23
	v_cvt_pk_bf16_f32 v23, v24, v25
	v_cvt_pk_bf16_f32 v26, v26, v27
	v_cvt_pk_bf16_f32 v27, v28, v29
	v_cvt_pk_bf16_f32 v30, v30, v31
	v_cvt_pk_bf16_f32 v31, v32, v33
	v_cvt_pk_bf16_f32 v34, v34, v35
	v_cvt_pk_bf16_f32 v35, v36, v37
	s_add_u32 s26, s22, 0x3000000
	s_addc_u32 s27, s23, 0
	global_store_dwordx2 v72, v[2:3], s[26:27]
	global_store_dwordx2 v73, v[6:7], s[26:27]
	global_store_dwordx2 v74, v[10:11], s[26:27]
	global_store_dwordx2 v75, v[14:15], s[26:27]
	global_store_dwordx2 v76, v[22:23], s[26:27]
	global_store_dwordx2 v77, v[26:27], s[26:27]
	global_store_dwordx2 v78, v[30:31], s[26:27]
	global_store_dwordx2 v79, v[34:35], s[26:27]
	s_waitcnt vmcnt(8)
	v_cvt_pk_bf16_f32 v48, v48, v49
	v_cvt_pk_bf16_f32 v49, v50, v51
	v_cvt_pk_bf16_f32 v52, v52, v53
	v_cvt_pk_bf16_f32 v53, v54, v55
	v_cvt_pk_bf16_f32 v56, v56, v57
	v_cvt_pk_bf16_f32 v57, v58, v59
	v_cvt_pk_bf16_f32 v60, v60, v61
	v_cvt_pk_bf16_f32 v61, v62, v63
	v_cvt_pk_bf16_f32 v100, v100, v101
	v_cvt_pk_bf16_f32 v101, v102, v103
	v_cvt_pk_bf16_f32 v104, v104, v105
	v_cvt_pk_bf16_f32 v105, v106, v107
	v_cvt_pk_bf16_f32 v108, v108, v109
	v_cvt_pk_bf16_f32 v109, v110, v111
	v_cvt_pk_bf16_f32 v112, v112, v113
	v_cvt_pk_bf16_f32 v113, v114, v115
	s_add_u32 s26, s22, 0x3800000
	s_addc_u32 s27, s23, 0
	global_store_dwordx2 v72, v[48:49], s[26:27]
	global_store_dwordx2 v73, v[52:53], s[26:27]
	global_store_dwordx2 v74, v[56:57], s[26:27]
	global_store_dwordx2 v75, v[60:61], s[26:27]
	global_store_dwordx2 v76, v[100:101], s[26:27]
	global_store_dwordx2 v77, v[104:105], s[26:27]
	global_store_dwordx2 v78, v[108:109], s[26:27]
	global_store_dwordx2 v79, v[112:113], s[26:27]
	s_branch .LBB0_121

; #define LAS __attribute__((address_space(3)))
; __device__ __forceinline__ int otid(int wv0) { int t = (wv0 << 6) | olane(); asm volatile("" : "+v"(t)); return t; }
; __device__ __forceinline__ int obid() { int b = blockIdx.x; asm volatile("" : "+s"(b)); return b; }
; __device__ __forceinline__ int ogrid() { int g = gridDim.x; asm volatile("" : "+s"(g)); return g; }
; #define CVT_LOAD(t_) do { const int k0_ = ((t_) % nkt) * 64, n0_ = ((t_) / nkt) * 64; const int sn = srcmap(kind, n0_ + nl); \
;     _Pragma("unroll") for (int i = 0; i < 8; ++i) { const int kl = kb + 8 * i; v[i] = 0.f; \
;       if (sn >= 0) { v[i] = src[(size_t)(k0_ + kl) * Nsrc + sn]; if (kscale) v[i] *= kscale[k0_ + kl]; } } } while (0)
; __device__ __forceinline__ void cvt_job(LAS unsigned char* lds, const float* src, bf16_t* dst, const float* kscale, int K, int Nsrc, int Ndst, int kind, int wv0, int bid_, int grd_) {
;   LAS float* tile = (LAS float*)lds;
;   const int tid = otid(wv0), nkt = K / 64, ntile = (Ndst / 64) * nkt;
;   if (bid_ < 0) return;
;   const int nl = tid & 63, kb = tid >> 6;
;   float v[8];
;     ...
;   if (bid_ < ntile) CVT_LOAD(bid_);
;   for (int t = bid_; t < ntile; t += grd_) {
;     const int k0 = (t % nkt) * 64, n0 = (t / nkt) * 64;
; #pragma unroll
;     for (int i = 0; i < 8; ++i) tile[(kb + 8 * i) * 65 + nl] = v[i];
;     __syncthreads();
;     if (t + grd_ < ntile) CVT_LOAD(t + grd_);
; __device__ __forceinline__ void cvt_ffn(KP p, int l, LAS unsigned char* lds, int wv0) {
;   unsigned char* W = p->ws; const int f = obid(), st = ogrid();
;   cvt_job(lds, p->w_up + (size_t)l * DM * NUP, (bf16_t*)(W + O_WUP), nullptr, DM, NUP, NUP, 4, wv0, f, st);
.LBB0_1163:
	s_or_b64 exec, exec, s[6:7]
	s_load_dwordx2 s[6:7], s[54:55], 0x98
	s_mul_i32 s2, s66, 0x5800000
	s_mul_hi_u32 s3, s66, 0x5800000
	s_mov_b32 s8, s4
	s_mov_b32 s9, s5
	s_waitcnt lgkmcnt(0)
	s_add_u32 s6, s6, s2
	s_addc_u32 s7, s7, s3
	v_mbcnt_lo_u32_b32 v43, -1, 0
	v_mbcnt_hi_u32_b32 v43, -1, v43
	v_or_b32_e32 v43, s1, v43
	v_and_b32_e32 v44, 63, v43
	v_lshrrev_b32_e32 v40, 6, v43
	s_mov_b32 s10, 0xb000
	v_mul_lo_u32 v32, v40, s10
	v_lshl_add_u32 v32, v44, 2, v32
	v_add_u32_e32 v33, 0x58000, v32
	v_add_u32_e32 v34, 0xb0000, v32
	v_add_u32_e32 v35, 0x108000, v32
	v_add_u32_e32 v36, 0x160000, v32
	v_add_u32_e32 v37, 0x1b8000, v32
	v_add_u32_e32 v38, 0x210000, v32
	v_add_u32_e32 v39, 0x268000, v32
	v_mul_u32_u24_e32 v40, 65, v40
	v_add_lshl_u32 v40, v40, v44, 2
	v_and_b32_e32 v44, 7, v43
	v_lshlrev_b32_e32 v44, 3, v44
	v_lshrrev_b32_e32 v43, 3, v43
	v_mul_u32_u24_e32 v41, 65, v44
	v_add_lshl_u32 v41, v41, v43, 2
	s_movk_i32 s10, 0x800
	v_mul_lo_u32 v42, v43, s10
	v_add_lshl_u32 v42, v42, v44, 1
	s_mov_b32 s11, s82
	s_lshl_b32 s12, s60, 2
	s_mov_b32 s13, 0
	s_add_u32 s13, s13, s11
	s_and_b32 s18, s13, 31
	s_lshr_b32 s19, s13, 5
	s_lshl_b32 s18, s18, 6
	s_lshl_b32 s19, s19, 6
	s_and_b32 s20, s19, 0xff
	s_lshr_b32 s21, s19, 8
	s_lshl_b32 s21, s21, 7
	s_add_u32 s21, s21, s20
	s_add_u32 s22, s21, 0x1580
	s_cmp_lt_u32 s20, 0x80
	s_cselect_b32 s21, s21, s22
	s_mul_i32 s20, s18, 0xb000
	s_lshl_b32 s21, s21, 2
	s_add_u32 s20, s20, s21
	s_add_u32 s14, s6, s20
	s_addc_u32 s15, s7, 0
	s_cmp_lt_u32 s13, 0x1600
	s_cbranch_scc0 .Lcvtup_pl
	global_load_dword v0, v32, s[14:15] nt
	global_load_dword v1, v33, s[14:15] nt
	global_load_dword v2, v34, s[14:15] nt
	global_load_dword v3, v35, s[14:15] nt
	global_load_dword v4, v36, s[14:15] nt
	global_load_dword v5, v37, s[14:15] nt
	global_load_dword v6, v38, s[14:15] nt
	global_load_dword v7, v39, s[14:15] nt
	s_mul_i32 s13, s60, 1
	s_add_u32 s13, s13, s11
	s_and_b32 s18, s13, 31
	s_lshr_b32 s19, s13, 5
	s_lshl_b32 s18, s18, 6
	s_lshl_b32 s19, s19, 6
	s_and_b32 s20, s19, 0xff
	s_lshr_b32 s21, s19, 8
	s_lshl_b32 s21, s21, 7
	s_add_u32 s21, s21, s20
	s_add_u32 s22, s21, 0x1580
	s_cmp_lt_u32 s20, 0x80
	s_cselect_b32 s21, s21, s22
	s_mul_i32 s20, s18, 0xb000
	s_lshl_b32 s21, s21, 2
	s_add_u32 s20, s20, s21
	s_add_u32 s14, s6, s20
	s_addc_u32 s15, s7, 0
	s_cmp_lt_u32 s13, 0x1600
	s_cbranch_scc0 .Lcvtup_pl
	global_load_dword v8, v32, s[14:15] nt
	global_load_dword v9, v33, s[14:15] nt
	global_load_dword v10, v34, s[14:15] nt
	global_load_dword v11, v35, s[14:15] nt
	global_load_dword v12, v36, s[14:15] nt
	global_load_dword v13, v37, s[14:15] nt
	global_load_dword v14, v38, s[14:15] nt
	global_load_dword v15, v39, s[14:15] nt
	s_mul_i32 s13, s60, 2
	s_add_u32 s13, s13, s11
	s_and_b32 s18, s13, 31
	s_lshr_b32 s19, s13, 5
	s_lshl_b32 s18, s18, 6
	s_lshl_b32 s19, s19, 6
	s_and_b32 s20, s19, 0xff
	s_lshr_b32 s21, s19, 8
	s_lshl_b32 s21, s21, 7
	s_add_u32 s21, s21, s20
	s_add_u32 s22, s21, 0x1580
	s_cmp_lt_u32 s20, 0x80
	s_cselect_b32 s21, s21, s22
	s_mul_i32 s20, s18, 0xb000
	s_lshl_b32 s21, s21, 2
	s_add_u32 s20, s20, s21
	s_add_u32 s14, s6, s20
	s_addc_u32 s15, s7, 0
	s_cmp_lt_u32 s13, 0x1600
	s_cbranch_scc0 .Lcvtup_pl
	global_load_dword v16, v32, s[14:15] nt
	global_load_dword v17, v33, s[14:15] nt
	global_load_dword v18, v34, s[14:15] nt
	global_load_dword v19, v35, s[14:15] nt
	global_load_dword v20, v36, s[14:15] nt
	global_load_dword v21, v37, s[14:15] nt
	global_load_dword v22, v38, s[14:15] nt
	global_load_dword v23, v39, s[14:15] nt
	s_mul_i32 s13, s60, 3
	s_add_u32 s13, s13, s11
	s_and_b32 s18, s13, 31
	s_lshr_b32 s19, s13, 5
	s_lshl_b32 s18, s18, 6
	s_lshl_b32 s19, s19, 6
	s_and_b32 s20, s19, 0xff
	s_lshr_b32 s21, s19, 8
	s_lshl_b32 s21, s21, 7
	s_add_u32 s21, s21, s20
	s_add_u32 s22, s21, 0x1580
	s_cmp_lt_u32 s20, 0x80
	s_cselect_b32 s21, s21, s22
	s_mul_i32 s20, s18, 0xb000
	s_lshl_b32 s21, s21, 2
	s_add_u32 s20, s20, s21
	s_add_u32 s14, s6, s20
	s_addc_u32 s15, s7, 0
	s_cmp_lt_u32 s13, 0x1600
	s_cbranch_scc0 .Lcvtup_pl
	global_load_dword v24, v32, s[14:15] nt
	global_load_dword v25, v33, s[14:15] nt
	global_load_dword v26, v34, s[14:15] nt
	global_load_dword v27, v35, s[14:15] nt
	global_load_dword v28, v36, s[14:15] nt
	global_load_dword v29, v37, s[14:15] nt
	global_load_dword v30, v38, s[14:15] nt
	global_load_dword v31, v39, s[14:15] nt

; #define CVT_LOAD(t_) do { const int k0_ = ((t_) % nkt) * 64, n0_ = ((t_) / nkt) * 64; const int sn = srcmap(kind, n0_ + nl); \
;     _Pragma("unroll") for (int i = 0; i < 8; ++i) { const int kl = kb + 8 * i; v[i] = 0.f; \
;       if (sn >= 0) { v[i] = src[(size_t)(k0_ + kl) * Nsrc + sn]; if (kscale) v[i] *= kscale[k0_ + kl]; } } } while (0)
; __device__ __forceinline__ void cvt_job(LAS unsigned char* lds, const float* src, bf16_t* dst, const float* kscale, int K, int Nsrc, int Ndst, int kind, int wv0, int bid_, int grd_) {
;     ...
;   for (int t = bid_; t < ntile; t += grd_) {
;     const int k0 = (t % nkt) * 64, n0 = (t / nkt) * 64;
; #pragma unroll
;     for (int i = 0; i < 8; ++i) tile[(kb + 8 * i) * 65 + nl] = v[i];
;     __syncthreads();
;     if (t + grd_ < ntile) CVT_LOAD(t + grd_);
.Lcvtup_wd:
	s_waitcnt lgkmcnt(0)
	s_barrier
	s_add_u32 s11, s11, s12
	s_mov_b32 s13, 0
	s_add_u32 s13, s13, s11
	s_and_b32 s18, s13, 31
	s_lshr_b32 s19, s13, 5
	s_lshl_b32 s18, s18, 6
	s_lshl_b32 s19, s19, 6
	s_and_b32 s20, s19, 0xff
	s_lshr_b32 s21, s19, 8
	s_lshl_b32 s21, s21, 7
	s_add_u32 s21, s21, s20
	s_add_u32 s22, s21, 0x1580
	s_cmp_lt_u32 s20, 0x80
	s_cselect_b32 s21, s21, s22
	s_mul_i32 s20, s18, 0xb000
	s_lshl_b32 s21, s21, 2
	s_add_u32 s20, s20, s21
	s_add_u32 s14, s6, s20
	s_addc_u32 s15, s7, 0
	s_cmp_lt_u32 s13, 0x1600
	s_cbranch_scc0 .Lcvtup_nl
	global_load_dword v0, v32, s[14:15] nt
	global_load_dword v1, v33, s[14:15] nt
	global_load_dword v2, v34, s[14:15] nt
	global_load_dword v3, v35, s[14:15] nt
	global_load_dword v4, v36, s[14:15] nt
	global_load_dword v5, v37, s[14:15] nt
	global_load_dword v6, v38, s[14:15] nt
	global_load_dword v7, v39, s[14:15] nt
	s_mul_i32 s13, s60, 1
	s_add_u32 s13, s13, s11
	s_and_b32 s18, s13, 31
	s_lshr_b32 s19, s13, 5
	s_lshl_b32 s18, s18, 6
	s_lshl_b32 s19, s19, 6
	s_and_b32 s20, s19, 0xff
	s_lshr_b32 s21, s19, 8
	s_lshl_b32 s21, s21, 7
	s_add_u32 s21, s21, s20
	s_add_u32 s22, s21, 0x1580
	s_cmp_lt_u32 s20, 0x80
	s_cselect_b32 s21, s21, s22
	s_mul_i32 s20, s18, 0xb000
	s_lshl_b32 s21, s21, 2
	s_add_u32 s20, s20, s21
	s_add_u32 s14, s6, s20
	s_addc_u32 s15, s7, 0
	s_cmp_lt_u32 s13, 0x1600
	s_cbranch_scc0 .Lcvtup_nl
	global_load_dword v8, v32, s[14:15] nt
	global_load_dword v9, v33, s[14:15] nt
	global_load_dword v10, v34, s[14:15] nt
	global_load_dword v11, v35, s[14:15] nt
	global_load_dword v12, v36, s[14:15] nt
	global_load_dword v13, v37, s[14:15] nt
	global_load_dword v14, v38, s[14:15] nt
	global_load_dword v15, v39, s[14:15] nt
	s_mul_i32 s13, s60, 2
	s_add_u32 s13, s13, s11
	s_and_b32 s18, s13, 31
	s_lshr_b32 s19, s13, 5
	s_lshl_b32 s18, s18, 6
	s_lshl_b32 s19, s19, 6
	s_and_b32 s20, s19, 0xff
	s_lshr_b32 s21, s19, 8
	s_lshl_b32 s21, s21, 7
	s_add_u32 s21, s21, s20
	s_add_u32 s22, s21, 0x1580
	s_cmp_lt_u32 s20, 0x80
	s_cselect_b32 s21, s21, s22
	s_mul_i32 s20, s18, 0xb000
	s_lshl_b32 s21, s21, 2
	s_add_u32 s20, s20, s21
	s_add_u32 s14, s6, s20
	s_addc_u32 s15, s7, 0
	s_cmp_lt_u32 s13, 0x1600
	s_cbranch_scc0 .Lcvtup_nl
	global_load_dword v16, v32, s[14:15] nt
	global_load_dword v17, v33, s[14:15] nt
	global_load_dword v18, v34, s[14:15] nt
	global_load_dword v19, v35, s[14:15] nt
	global_load_dword v20, v36, s[14:15] nt
	global_load_dword v21, v37, s[14:15] nt
	global_load_dword v22, v38, s[14:15] nt
	global_load_dword v23, v39, s[14:15] nt
	s_mul_i32 s13, s60, 3
	s_add_u32 s13, s13, s11
	s_and_b32 s18, s13, 31
	s_lshr_b32 s19, s13, 5
	s_lshl_b32 s18, s18, 6
	s_lshl_b32 s19, s19, 6
	s_and_b32 s20, s19, 0xff
	s_lshr_b32 s21, s19, 8
	s_lshl_b32 s21, s21, 7
	s_add_u32 s21, s21, s20
	s_add_u32 s22, s21, 0x1580
	s_cmp_lt_u32 s20, 0x80
	s_cselect_b32 s21, s21, s22
	s_mul_i32 s20, s18, 0xb000
	s_lshl_b32 s21, s21, 2
	s_add_u32 s20, s20, s21
	s_add_u32 s14, s6, s20
	s_addc_u32 s15, s7, 0
	s_cmp_lt_u32 s13, 0x1600
	s_cbranch_scc0 .Lcvtup_nl
	global_load_dword v24, v32, s[14:15] nt
	global_load_dword v25, v33, s[14:15] nt
	global_load_dword v26, v34, s[14:15] nt
	global_load_dword v27, v35, s[14:15] nt
	global_load_dword v28, v36, s[14:15] nt
	global_load_dword v29, v37, s[14:15] nt
	global_load_dword v30, v38, s[14:15] nt
	global_load_dword v31, v39, s[14:15] nt

; #define LAS __attribute__((address_space(3)))
; __device__ __forceinline__ int otid(int wv0) { int t = (wv0 << 6) | olane(); asm volatile("" : "+v"(t)); return t; }
; #define CVT_LOAD(t_) do { const int k0_ = ((t_) % nkt) * 64, n0_ = ((t_) / nkt) * 64; const int sn = srcmap(kind, n0_ + nl); \
;     _Pragma("unroll") for (int i = 0; i < 8; ++i) { const int kl = kb + 8 * i; v[i] = 0.f; \
;       if (sn >= 0) { v[i] = src[(size_t)(k0_ + kl) * Nsrc + sn]; if (kscale) v[i] *= kscale[k0_ + kl]; } } } while (0)
; __device__ __forceinline__ void cvt_job(LAS unsigned char* lds, const float* src, bf16_t* dst, const float* kscale, int K, int Nsrc, int Ndst, int kind, int wv0, int bid_, int grd_) {
;   LAS float* tile = (LAS float*)lds;
;   const int tid = otid(wv0), nkt = K / 64, ntile = (Ndst / 64) * nkt;
;   if (bid_ < 0) return;
;   const int nl = tid & 63, kb = tid >> 6;
;   float v[8];
;     ...
;   if (bid_ < ntile) CVT_LOAD(bid_);
; __device__ __forceinline__ void cvt_ffn(KP p, int l, LAS unsigned char* lds, int wv0) {
;     ...
;   cvt_job(lds, p->w_down + (size_t)l * DFF * DM, (bf16_t*)(W + O_WDN), nullptr, DFF, DM, DM, 0, wv0, f, st);
.Lcvtup_end:
	s_waitcnt vmcnt(0)
	s_load_dwordx2 s[6:7], s[54:55], 0xb0
	s_mul_i32 s2, s66, 0x2c00000
	s_mul_hi_u32 s3, s66, 0x2c00000
	s_add_u32 s8, s4, 0x2c00000
	s_addc_u32 s9, s5, 0
	s_waitcnt lgkmcnt(0)
	s_add_u32 s6, s6, s2
	s_addc_u32 s7, s7, s3
	v_mbcnt_lo_u32_b32 v43, -1, 0
	v_mbcnt_hi_u32_b32 v43, -1, v43
	v_or_b32_e32 v43, s1, v43
	v_and_b32_e32 v44, 63, v43
	v_lshrrev_b32_e32 v40, 6, v43
	s_mov_b32 s10, 0x2000
	v_mul_lo_u32 v32, v40, s10
	v_lshl_add_u32 v32, v44, 2, v32
	v_add_u32_e32 v33, 0x10000, v32
	v_add_u32_e32 v34, 0x20000, v32
	v_add_u32_e32 v35, 0x30000, v32
	v_add_u32_e32 v36, 0x40000, v32
	v_add_u32_e32 v37, 0x50000, v32
	v_add_u32_e32 v38, 0x60000, v32
	v_add_u32_e32 v39, 0x70000, v32
	v_mul_u32_u24_e32 v40, 65, v40
	v_add_lshl_u32 v40, v40, v44, 2
	v_and_b32_e32 v44, 7, v43
	v_lshlrev_b32_e32 v44, 3, v44
	v_lshrrev_b32_e32 v43, 3, v43
	v_mul_u32_u24_e32 v41, 65, v44
	v_add_lshl_u32 v41, v41, v43, 2
	s_movk_i32 s10, 0x1600
	v_mul_lo_u32 v42, v43, s10
	v_add_lshl_u32 v42, v42, v44, 1
	s_mov_b32 s11, s82
	s_lshl_b32 s12, s60, 2
	s_mov_b32 s13, 0
	s_add_u32 s13, s13, s11
	s_mul_i32 s19, s13, 0xba2f
	s_lshr_b32 s19, s19, 22
	s_mul_i32 s18, s19, 88
	s_sub_u32 s18, s13, s18
	s_lshl_b32 s18, s18, 6
	s_lshl_b32 s19, s19, 6
	s_mov_b32 s21, s19
	s_mul_i32 s20, s18, 0x2000
	s_lshl_b32 s21, s21, 2
	s_add_u32 s20, s20, s21
	s_add_u32 s14, s6, s20
	s_addc_u32 s15, s7, 0
	s_cmp_lt_u32 s13, 0xb00
	s_cbranch_scc0 .Lcvtdn_pl
	global_load_dword v0, v32, s[14:15] nt
	global_load_dword v1, v33, s[14:15] nt
	global_load_dword v2, v34, s[14:15] nt
	global_load_dword v3, v35, s[14:15] nt
	global_load_dword v4, v36, s[14:15] nt
	global_load_dword v5, v37, s[14:15] nt
	global_load_dword v6, v38, s[14:15] nt
	global_load_dword v7, v39, s[14:15] nt
	s_mul_i32 s13, s60, 1
	s_add_u32 s13, s13, s11
	s_mul_i32 s19, s13, 0xba2f
	s_lshr_b32 s19, s19, 22
	s_mul_i32 s18, s19, 88
	s_sub_u32 s18, s13, s18
	s_lshl_b32 s18, s18, 6
	s_lshl_b32 s19, s19, 6
	s_mov_b32 s21, s19
	s_mul_i32 s20, s18, 0x2000
	s_lshl_b32 s21, s21, 2
	s_add_u32 s20, s20, s21
	s_add_u32 s14, s6, s20
	s_addc_u32 s15, s7, 0
	s_cmp_lt_u32 s13, 0xb00
	s_cbranch_scc0 .Lcvtdn_pl
	global_load_dword v8, v32, s[14:15] nt
	global_load_dword v9, v33, s[14:15] nt
	global_load_dword v10, v34, s[14:15] nt
	global_load_dword v11, v35, s[14:15] nt
	global_load_dword v12, v36, s[14:15] nt
	global_load_dword v13, v37, s[14:15] nt
	global_load_dword v14, v38, s[14:15] nt
	global_load_dword v15, v39, s[14:15] nt
	s_mul_i32 s13, s60, 2
	s_add_u32 s13, s13, s11
	s_mul_i32 s19, s13, 0xba2f
	s_lshr_b32 s19, s19, 22
	s_mul_i32 s18, s19, 88
	s_sub_u32 s18, s13, s18
	s_lshl_b32 s18, s18, 6
	s_lshl_b32 s19, s19, 6
	s_mov_b32 s21, s19
	s_mul_i32 s20, s18, 0x2000
	s_lshl_b32 s21, s21, 2
	s_add_u32 s20, s20, s21
	s_add_u32 s14, s6, s20
	s_addc_u32 s15, s7, 0
	s_cmp_lt_u32 s13, 0xb00
	s_cbranch_scc0 .Lcvtdn_pl
	global_load_dword v16, v32, s[14:15] nt
	global_load_dword v17, v33, s[14:15] nt
	global_load_dword v18, v34, s[14:15] nt
	global_load_dword v19, v35, s[14:15] nt
	global_load_dword v20, v36, s[14:15] nt
	global_load_dword v21, v37, s[14:15] nt
	global_load_dword v22, v38, s[14:15] nt
	global_load_dword v23, v39, s[14:15] nt
	s_mul_i32 s13, s60, 3
	s_add_u32 s13, s13, s11
	s_mul_i32 s19, s13, 0xba2f
	s_lshr_b32 s19, s19, 22
	s_mul_i32 s18, s19, 88
	s_sub_u32 s18, s13, s18
	s_lshl_b32 s18, s18, 6
	s_lshl_b32 s19, s19, 6
	s_mov_b32 s21, s19
	s_mul_i32 s20, s18, 0x2000
	s_lshl_b32 s21, s21, 2
	s_add_u32 s20, s20, s21
	s_add_u32 s14, s6, s20
	s_addc_u32 s15, s7, 0
	s_cmp_lt_u32 s13, 0xb00
	s_cbranch_scc0 .Lcvtdn_pl
	global_load_dword v24, v32, s[14:15] nt
	global_load_dword v25, v33, s[14:15] nt
	global_load_dword v26, v34, s[14:15] nt
	global_load_dword v27, v35, s[14:15] nt
	global_load_dword v28, v36, s[14:15] nt
	global_load_dword v29, v37, s[14:15] nt
	global_load_dword v30, v38, s[14:15] nt
	global_load_dword v31, v39, s[14:15] nt

; #define CVT_LOAD(t_) do { const int k0_ = ((t_) % nkt) * 64, n0_ = ((t_) / nkt) * 64; const int sn = srcmap(kind, n0_ + nl); \
;     _Pragma("unroll") for (int i = 0; i < 8; ++i) { const int kl = kb + 8 * i; v[i] = 0.f; \
;       if (sn >= 0) { v[i] = src[(size_t)(k0_ + kl) * Nsrc + sn]; if (kscale) v[i] *= kscale[k0_ + kl]; } } } while (0)
; __device__ __forceinline__ void cvt_job(LAS unsigned char* lds, const float* src, bf16_t* dst, const float* kscale, int K, int Nsrc, int Ndst, int kind, int wv0, int bid_, int grd_) {
;     ...
;   for (int t = bid_; t < ntile; t += grd_) {
;     const int k0 = (t % nkt) * 64, n0 = (t / nkt) * 64;
; #pragma unroll
;     for (int i = 0; i < 8; ++i) tile[(kb + 8 * i) * 65 + nl] = v[i];
;     __syncthreads();
;     if (t + grd_ < ntile) CVT_LOAD(t + grd_);
.Lcvtdn_wd:
	s_waitcnt lgkmcnt(0)
	s_barrier
	s_add_u32 s11, s11, s12
	s_mov_b32 s13, 0
	s_add_u32 s13, s13, s11
	s_mul_i32 s19, s13, 0xba2f
	s_lshr_b32 s19, s19, 22
	s_mul_i32 s18, s19, 88
	s_sub_u32 s18, s13, s18
	s_lshl_b32 s18, s18, 6
	s_lshl_b32 s19, s19, 6
	s_mov_b32 s21, s19
	s_mul_i32 s20, s18, 0x2000
	s_lshl_b32 s21, s21, 2
	s_add_u32 s20, s20, s21
	s_add_u32 s14, s6, s20
	s_addc_u32 s15, s7, 0
	s_cmp_lt_u32 s13, 0xb00
	s_cbranch_scc0 .Lcvtdn_nl
	global_load_dword v0, v32, s[14:15] nt
	global_load_dword v1, v33, s[14:15] nt
	global_load_dword v2, v34, s[14:15] nt
	global_load_dword v3, v35, s[14:15] nt
	global_load_dword v4, v36, s[14:15] nt
	global_load_dword v5, v37, s[14:15] nt
	global_load_dword v6, v38, s[14:15] nt
	global_load_dword v7, v39, s[14:15] nt
	s_mul_i32 s13, s60, 1
	s_add_u32 s13, s13, s11
	s_mul_i32 s19, s13, 0xba2f
	s_lshr_b32 s19, s19, 22
	s_mul_i32 s18, s19, 88
	s_sub_u32 s18, s13, s18
	s_lshl_b32 s18, s18, 6
	s_lshl_b32 s19, s19, 6
	s_mov_b32 s21, s19
	s_mul_i32 s20, s18, 0x2000
	s_lshl_b32 s21, s21, 2
	s_add_u32 s20, s20, s21
	s_add_u32 s14, s6, s20
	s_addc_u32 s15, s7, 0
	s_cmp_lt_u32 s13, 0xb00
	s_cbranch_scc0 .Lcvtdn_nl
	global_load_dword v8, v32, s[14:15] nt
	global_load_dword v9, v33, s[14:15] nt
	global_load_dword v10, v34, s[14:15] nt
	global_load_dword v11, v35, s[14:15] nt
	global_load_dword v12, v36, s[14:15] nt
	global_load_dword v13, v37, s[14:15] nt
	global_load_dword v14, v38, s[14:15] nt
	global_load_dword v15, v39, s[14:15] nt
	s_mul_i32 s13, s60, 2
	s_add_u32 s13, s13, s11
	s_mul_i32 s19, s13, 0xba2f
	s_lshr_b32 s19, s19, 22
	s_mul_i32 s18, s19, 88
	s_sub_u32 s18, s13, s18
	s_lshl_b32 s18, s18, 6
	s_lshl_b32 s19, s19, 6
	s_mov_b32 s21, s19
	s_mul_i32 s20, s18, 0x2000
	s_lshl_b32 s21, s21, 2
	s_add_u32 s20, s20, s21
	s_add_u32 s14, s6, s20
	s_addc_u32 s15, s7, 0
	s_cmp_lt_u32 s13, 0xb00
	s_cbranch_scc0 .Lcvtdn_nl
	global_load_dword v16, v32, s[14:15] nt
	global_load_dword v17, v33, s[14:15] nt
	global_load_dword v18, v34, s[14:15] nt
	global_load_dword v19, v35, s[14:15] nt
	global_load_dword v20, v36, s[14:15] nt
	global_load_dword v21, v37, s[14:15] nt
	global_load_dword v22, v38, s[14:15] nt
	global_load_dword v23, v39, s[14:15] nt
	s_mul_i32 s13, s60, 3
	s_add_u32 s13, s13, s11
	s_mul_i32 s19, s13, 0xba2f
	s_lshr_b32 s19, s19, 22
	s_mul_i32 s18, s19, 88
	s_sub_u32 s18, s13, s18
	s_lshl_b32 s18, s18, 6
	s_lshl_b32 s19, s19, 6
	s_mov_b32 s21, s19
	s_mul_i32 s20, s18, 0x2000
	s_lshl_b32 s21, s21, 2
	s_add_u32 s20, s20, s21
	s_add_u32 s14, s6, s20
	s_addc_u32 s15, s7, 0
	s_cmp_lt_u32 s13, 0xb00
	s_cbranch_scc0 .Lcvtdn_nl
	global_load_dword v24, v32, s[14:15] nt
	global_load_dword v25, v33, s[14:15] nt
	global_load_dword v26, v34, s[14:15] nt
	global_load_dword v27, v35, s[14:15] nt
	global_load_dword v28, v36, s[14:15] nt
	global_load_dword v29, v37, s[14:15] nt
	global_load_dword v30, v38, s[14:15] nt
	global_load_dword v31, v39, s[14:15] nt

; #define LAS __attribute__((address_space(3)))
; __device__ __forceinline__ int otid(int wv0) { int t = (wv0 << 6) | olane(); asm volatile("" : "+v"(t)); return t; }
; #define CVT_LOAD(t_) do { const int k0_ = ((t_) % nkt) * 64, n0_ = ((t_) / nkt) * 64; const int sn = srcmap(kind, n0_ + nl); \
;     _Pragma("unroll") for (int i = 0; i < 8; ++i) { const int kl = kb + 8 * i; v[i] = 0.f; \
;       if (sn >= 0) { v[i] = src[(size_t)(k0_ + kl) * Nsrc + sn]; if (kscale) v[i] *= kscale[k0_ + kl]; } } } while (0)
; __device__ __forceinline__ void cvt_job(LAS unsigned char* lds, const float* src, bf16_t* dst, const float* kscale, int K, int Nsrc, int Ndst, int kind, int wv0, int bid_, int grd_) {
;   LAS float* tile = (LAS float*)lds;
;   const int tid = otid(wv0), nkt = K / 64, ntile = (Ndst / 64) * nkt;
;   if (bid_ < 0) return;
;   const int nl = tid & 63, kb = tid >> 6;
;   float v[8];
;     ...
;   if (bid_ < ntile) CVT_LOAD(bid_);
; __device__ __forceinline__ void cvt_mixer_a(KP p, int l, LAS unsigned char* lds, int wv0) {
;     ...
;   cvt_job(lds, p->w_in + (size_t)l * DM * NIN, (bf16_t*)(W + O_WG), nullptr, DM, NIN, NG, 2, wv0, f, st);
.Lmxa_end:
	s_waitcnt vmcnt(0)
	s_add_u32 s18, s8, 0x1200000
	s_addc_u32 s19, s9, 0
	v_mbcnt_lo_u32_b32 v235, -1, 0
	v_mbcnt_hi_u32_b32 v235, -1, v235
	v_or_b32_e32 v235, s22, v235
	v_and_b32_e32 v236, 63, v235
	v_lshrrev_b32_e32 v216, 6, v235
	s_mov_b32 s30, 0xa500
	v_mul_lo_u32 v208, v216, s30
	v_lshl_add_u32 v208, v236, 2, v208
	v_add_u32_e32 v209, 0x52800, v208
	v_add_u32_e32 v210, 0xa5000, v208
	v_add_u32_e32 v211, 0xf7800, v208
	v_add_u32_e32 v212, 0x14a000, v208
	v_add_u32_e32 v213, 0x19c800, v208
	v_add_u32_e32 v214, 0x1ef000, v208
	v_add_u32_e32 v215, 0x241800, v208
	v_mul_u32_u24_e32 v216, 65, v216
	v_add_lshl_u32 v216, v216, v236, 2
	v_and_b32_e32 v236, 7, v235
	v_lshlrev_b32_e32 v236, 3, v236
	v_lshrrev_b32_e32 v235, 3, v235
	v_mul_u32_u24_e32 v217, 65, v236
	v_add_lshl_u32 v217, v217, v235, 2
	s_movk_i32 s30, 0x800
	v_mul_lo_u32 v234, v235, s30
	v_add_lshl_u32 v234, v234, v236, 1
	s_mov_b32 s20, s82
	s_lshl_b32 s21, s60, 2
	s_mov_b32 s23, 0
	s_add_u32 s23, s23, s20
	s_and_b32 s28, s23, 31
	s_lshr_b32 s29, s23, 5
	s_lshl_b32 s28, s28, 6
	s_lshl_b32 s29, s29, 6
	s_mov_b32 s13, 0
	s_add_u32 s31, s29, 0x1140
	s_mul_i32 s12, s28, 0xa500
	s_lshl_b32 s31, s31, 2
	s_add_u32 s12, s12, s31
	s_add_u32 s24, s16, s12
	s_addc_u32 s25, s17, 0
	s_cmp_lt_u32 s23, 0xc00
	s_cbranch_scc0 .Lmxg_pl
	global_load_dword v176, v208, s[24:25] nt
	global_load_dword v177, v209, s[24:25] nt
	global_load_dword v178, v210, s[24:25] nt
	global_load_dword v179, v211, s[24:25] nt
	global_load_dword v180, v212, s[24:25] nt
	global_load_dword v181, v213, s[24:25] nt
	global_load_dword v182, v214, s[24:25] nt
	global_load_dword v183, v215, s[24:25] nt
	s_mul_i32 s23, s60, 1
	s_add_u32 s23, s23, s20
	s_and_b32 s28, s23, 31
	s_lshr_b32 s29, s23, 5
	s_lshl_b32 s28, s28, 6
	s_lshl_b32 s29, s29, 6
	s_mov_b32 s13, 0
	s_add_u32 s31, s29, 0x1140
	s_mul_i32 s12, s28, 0xa500
	s_lshl_b32 s31, s31, 2
	s_add_u32 s12, s12, s31
	s_add_u32 s24, s16, s12
	s_addc_u32 s25, s17, 0
	s_cmp_lt_u32 s23, 0xc00
	s_cbranch_scc0 .Lmxg_pl
	global_load_dword v184, v208, s[24:25] nt
	global_load_dword v185, v209, s[24:25] nt
	global_load_dword v186, v210, s[24:25] nt
	global_load_dword v187, v211, s[24:25] nt
	global_load_dword v188, v212, s[24:25] nt
	global_load_dword v189, v213, s[24:25] nt
	global_load_dword v190, v214, s[24:25] nt
	global_load_dword v191, v215, s[24:25] nt
	s_mul_i32 s23, s60, 2
	s_add_u32 s23, s23, s20
	s_and_b32 s28, s23, 31
	s_lshr_b32 s29, s23, 5
	s_lshl_b32 s28, s28, 6
	s_lshl_b32 s29, s29, 6
	s_mov_b32 s13, 0
	s_add_u32 s31, s29, 0x1140
	s_mul_i32 s12, s28, 0xa500
	s_lshl_b32 s31, s31, 2
	s_add_u32 s12, s12, s31
	s_add_u32 s24, s16, s12
	s_addc_u32 s25, s17, 0
	s_cmp_lt_u32 s23, 0xc00
	s_cbranch_scc0 .Lmxg_pl
	global_load_dword v192, v208, s[24:25] nt
	global_load_dword v193, v209, s[24:25] nt
	global_load_dword v194, v210, s[24:25] nt
	global_load_dword v195, v211, s[24:25] nt
	global_load_dword v196, v212, s[24:25] nt
	global_load_dword v197, v213, s[24:25] nt
	global_load_dword v198, v214, s[24:25] nt
	global_load_dword v199, v215, s[24:25] nt
	s_mul_i32 s23, s60, 3
	s_add_u32 s23, s23, s20
	s_and_b32 s28, s23, 31
	s_lshr_b32 s29, s23, 5
	s_lshl_b32 s28, s28, 6
	s_lshl_b32 s29, s29, 6
	s_mov_b32 s13, 0
	s_add_u32 s31, s29, 0x1140
	s_mul_i32 s12, s28, 0xa500
	s_lshl_b32 s31, s31, 2
	s_add_u32 s12, s12, s31
	s_add_u32 s24, s16, s12
	s_addc_u32 s25, s17, 0
	s_cmp_lt_u32 s23, 0xc00
	s_cbranch_scc0 .Lmxg_pl
	global_load_dword v200, v208, s[24:25] nt
	global_load_dword v201, v209, s[24:25] nt
	global_load_dword v202, v210, s[24:25] nt
	global_load_dword v203, v211, s[24:25] nt
	global_load_dword v204, v212, s[24:25] nt
	global_load_dword v205, v213, s[24:25] nt
	global_load_dword v206, v214, s[24:25] nt
	global_load_dword v207, v215, s[24:25] nt
